# down-projection epilogue: ssin of the first row group loaded into a free pair so the other residual/ssin loads issue before the wait (one round trip per half)
# speedup vs baseline: 1.0018x; 1.0018x over previous
;     __device__ __forceinline__ void operator()(const f32x4 (&acc)[2][2][4][2], const Unit& u, int wr, int wc, int fr, int fq) const {
;     ...
;             u32x4 b[4][2]; unsigned long long sv[4];
; #pragma unroll
;             for (int m = 0; m < 4; ++m) { const bf16_t* bp = xb + (size_t)(row0 + ai * HALF + m * 16) * ldc + col0;
; #pragma unroll
;                 for (int bj = 0; bj < 2; ++bj) b[m][bj] = *(const u32x4*)(bp + bj * HALF);
;                 sv[m] = ssin ? ssin[row0 + ai * HALF + m * 16] : 0ull; }
; #pragma unroll
;             for (int m = 0; m < 4; ++m) { const int row = row0 + ai * HALF + m * 16; bf16_t* xp = xb + (size_t)row * ldc + col0;
;                 const float sc = ssin ? 1.0f / ((float)sv[m] * (1.f / (16777216.f * 2048.f)) + 1e-6f) : 1.f;
;                 float q = 0.f;
; #pragma unroll
;                 for (int bj = 0; bj < 2; ++bj) { f32x4 v0, v1;
; #pragma unroll
;                     for (int e = 0; e < 2; ++e) { v0[2 * e] = __builtin_bit_cast(float, b[m][bj][e] << 16); v0[2 * e + 1] = __builtin_bit_cast(float, b[m][bj][e] & 0xffff0000u);
;                                                   v1[2 * e] = __builtin_bit_cast(float, b[m][bj][2 + e] << 16); v1[2 * e + 1] = __builtin_bit_cast(float, b[m][bj][2 + e] & 0xffff0000u); }
;                     v0 += acc[ai][bj][m][0] * sc; v1 += acc[ai][bj][m][1] * sc;
.LBB0_959:
	s_lshl_b32 s52, s41, 8
	s_add_i32 s52, s52, s35
	v_lshl_or_b32 v172, s40, 8, v213
	v_or_b32_e32 v178, s52, v211
	v_ashrrev_i32_e32 v173, 31, v172
	v_lshlrev_b64 v[192:193], 1, v[172:173]
	v_ashrrev_i32_e32 v179, 31, v178
	v_lshl_add_u64 v[176:177], s[14:15], 0, v[192:193]
	v_lshlrev_b64 v[194:195], 12, v[178:179]
	v_lshl_add_u64 v[132:133], v[176:177], 0, v[194:195]
	v_lshl_add_u64 v[174:175], v[178:179], 3, s[10:11]
	global_load_dwordx4 v[168:171], v[132:133], off
	global_load_dwordx4 v[156:159], v[132:133], off offset:256
	v_or_b32_e32 v188, 16, v178
	global_load_dwordx2 v[222:223], v[174:175], off
	v_ashrrev_i32_e32 v189, 31, v188
	v_lshlrev_b64 v[196:197], 11, v[178:179]
	v_or_b32_e32 v184, 32, v178
	v_ashrrev_i32_e32 v185, 31, v184
	v_or_b32_e32 v180, 48, v178
	v_ashrrev_i32_e32 v181, 31, v180
	v_lshl_add_u64 v[182:183], v[180:181], 3, s[10:11]
	v_lshl_add_u64 v[196:197], v[196:197], 2, s[8:9]
	v_lshlrev_b64 v[132:133], 12, v[188:189]
	v_lshl_add_u64 v[132:133], v[176:177], 0, v[132:133]
	global_load_dwordx4 v[152:155], v[132:133], off
	global_load_dwordx4 v[148:151], v[132:133], off offset:256
	v_lshl_add_u64 v[132:133], v[188:189], 3, s[10:11]
	global_load_dwordx2 v[190:191], v[132:133], off
	v_lshlrev_b64 v[132:133], 12, v[184:185]
	v_lshl_add_u64 v[132:133], v[176:177], 0, v[132:133]
	global_load_dwordx4 v[144:147], v[132:133], off
	global_load_dwordx4 v[140:143], v[132:133], off offset:256
	v_lshl_add_u64 v[132:133], v[184:185], 3, s[10:11]
	global_load_dwordx2 v[186:187], v[132:133], off
	v_lshlrev_b64 v[132:133], 12, v[180:181]
	v_lshl_add_u64 v[132:133], v[176:177], 0, v[132:133]
	global_load_dwordx4 v[136:139], v[132:133], off
	s_nop 0
	global_load_dwordx4 v[132:135], v[132:133], off offset:256
	global_load_dwordx2 v[182:183], v[182:183], off
	s_waitcnt vmcnt(11)
	v_and_b32_e32 v221, 0xffff0000, v170
	s_waitcnt vmcnt(9)
	v_ffbh_u32_e32 v226, v223
	v_min_u32_e32 v226, 32, v226
	v_lshlrev_b64 v[224:225], v226, v[222:223]
	v_min_u32_e32 v224, 1, v224
	v_or_b32_e32 v224, v225, v224
	v_cvt_f32_u32_e32 v224, v224
	v_sub_u32_e32 v225, 32, v226
	v_ldexp_f32 v224, v224, v225
	v_fmamk_f32 v179, v224, 0x2e000000, v200
	v_div_scale_f32 v198, s[0:1], v179, v179, 1.0
	v_rcp_f32_e32 v199, v198
	s_nop 0
	v_fma_f32 v218, -v198, v199, 1.0
	v_fmac_f32_e32 v199, v218, v199
	v_div_scale_f32 v218, vcc, 1.0, v179, 1.0
	v_mul_f32_e32 v219, v218, v199
	v_fma_f32 v220, -v198, v219, v218
	v_fmac_f32_e32 v219, v220, v199
	v_fma_f32 v198, -v198, v219, v218
	v_div_fmas_f32 v198, v198, v199, v219
	v_div_fixup_f32 v198, v198, v179, 1.0
	v_lshlrev_b32_e32 v218, 16, v168
	v_and_b32_e32 v219, 0xffff0000, v168
	v_lshlrev_b32_e32 v168, 16, v169
	v_and_b32_e32 v169, 0xffff0000, v169
	v_lshlrev_b32_e32 v220, 16, v170
	v_lshlrev_b32_e32 v170, 16, v171
	v_and_b32_e32 v171, 0xffff0000, v171
	v_pk_fma_f32 v[130:131], v[130:131], v[198:199], v[168:169] op_sel_hi:[1,0,1]
	v_cndmask_b32_e64 v168, 0, 1, s[18:19]
	v_pk_fma_f32 v[128:129], v[128:129], v[198:199], v[218:219] op_sel_hi:[1,0,1]
	v_pk_fma_f32 v[126:127], v[126:127], v[198:199], v[170:171] op_sel_hi:[1,0,1]
	v_pk_fma_f32 v[124:125], v[124:125], v[198:199], v[220:221] op_sel_hi:[1,0,1]
	v_cmp_ne_u32_e64 s[40:41], 1, v168
	s_andn2_b64 vcc, exec, s[18:19]
	s_cbranch_vccnz .LBB0_1030
	v_lshl_add_u64 v[168:169], v[172:173], 2, v[196:197]
	global_store_dwordx4 v[168:169], v[128:131], off
	global_store_dwordx4 v[168:169], v[124:127], off offset:16
	v_lshl_add_u64 v[168:169], s[14:15], 0, v[194:195]
	v_lshl_add_u64 v[192:193], v[168:169], 0, v[192:193]
	s_cbranch_execnz .LBB0_962

;     __device__ __forceinline__ void operator()(const f32x4 (&acc)[2][2][4][2], const Unit& u, int wr, int wc, int fr, int fq) const {
;     ...
;             u32x4 b[4][2]; unsigned long long sv[4];
; #pragma unroll
;             for (int m = 0; m < 4; ++m) { const bf16_t* bp = xb + (size_t)(row0 + ai * HALF + m * 16) * ldc + col0;
; #pragma unroll
;                 for (int bj = 0; bj < 2; ++bj) b[m][bj] = *(const u32x4*)(bp + bj * HALF);
;                 sv[m] = ssin ? ssin[row0 + ai * HALF + m * 16] : 0ull; }
; #pragma unroll
;             for (int m = 0; m < 4; ++m) { const int row = row0 + ai * HALF + m * 16; bf16_t* xp = xb + (size_t)row * ldc + col0;
;                 const float sc = ssin ? 1.0f / ((float)sv[m] * (1.f / (16777216.f * 2048.f)) + 1e-6f) : 1.f;
;                 float q = 0.f;
; #pragma unroll
;                 for (int bj = 0; bj < 2; ++bj) { f32x4 v0, v1;
; #pragma unroll
;                     for (int e = 0; e < 2; ++e) { v0[2 * e] = __builtin_bit_cast(float, b[m][bj][e] << 16); v0[2 * e + 1] = __builtin_bit_cast(float, b[m][bj][e] & 0xffff0000u);
;                                                   v1[2 * e] = __builtin_bit_cast(float, b[m][bj][2 + e] << 16); v1[2 * e + 1] = __builtin_bit_cast(float, b[m][bj][2 + e] & 0xffff0000u); }
;                     v0 += acc[ai][bj][m][0] * sc; v1 += acc[ai][bj][m][1] * sc;
;                     q = __builtin_fmaf(v0[0], v0[0], q); q = __builtin_fmaf(v0[1], v0[1], q); q = __builtin_fmaf(v0[2], v0[2], q); q = __builtin_fmaf(v0[3], v0[3], q);
;                     q = __builtin_fmaf(v1[0], v1[0], q); q = __builtin_fmaf(v1[1], v1[1], q); q = __builtin_fmaf(v1[2], v1[2], q); q = __builtin_fmaf(v1[3], v1[3], q);
;                     if (outf) { float* op = outf + (size_t)row * ldc + col0 + bj * HALF; *(f32x4*)op = v0; *(f32x4*)(op + 4) = v1; }
;                     else { u32x4 w; w.x = cvt_pk_bf16(v0[0], v0[1]); w.y = cvt_pk_bf16(v0[2], v0[3]); w.z = cvt_pk_bf16(v1[0], v1[1]); w.w = cvt_pk_bf16(v1[2], v1[3]); *(u32x4*)(xp + bj * HALF) = w; } }
;                 sq[ai][m] = q; }
;             asm volatile("" ::: "memory");
; #pragma unroll
;             for (int m = 0; m < 4; ++m) { float q = sq[ai][m]; q = fq_sum(q); sq[ai][m] = q; }
;             const float v = fq == 0 ? sq[ai][0] : (fq == 1 ? sq[ai][1] : (fq == 2 ? sq[ai][2] : sq[ai][3]));
.LBB0_993:
	s_or_b64 exec, exec, s[0:1]
	v_add_f32_e32 v70, v68, v69
	v_mul_f32_e32 v70, 0x4b800000, v70
	v_trunc_f32_e32 v70, v70
	v_mul_f32_e32 v71, 0x2f800000, v70
	v_floor_f32_e32 v71, v71
	v_fmac_f32_e32 v70, 0xcf800000, v71
	v_cvt_u32_f32_e32 v70, v70
	v_cvt_u32_f32_e32 v71, v71
	v_or_b32_e32 v100, s52, v212
	v_ashrrev_i32_e32 v101, 31, v100
	v_lshl_add_u64 v[68:69], v[100:101], 3, s[12:13]
	global_atomic_add_x2 v[68:69], v[70:71], off
	v_add_u32_e32 v68, 0x80, v178
	v_ashrrev_i32_e32 v69, 31, v68
	v_lshlrev_b64 v[114:115], 12, v[68:69]
	v_lshlrev_b64 v[116:117], 11, v[68:69]
	v_lshl_add_u64 v[68:69], v[176:177], 0, v[114:115]
	global_load_dwordx4 v[96:99], v[68:69], off
	global_load_dwordx4 v[92:95], v[68:69], off offset:256
	s_nop 0
	global_load_dwordx2 v[228:229], v[174:175], off offset:1024
	v_add_u32_e32 v110, 0x90, v178
	v_ashrrev_i32_e32 v111, 31, v110
	v_add_u32_e32 v106, 0xa0, v178
	v_ashrrev_i32_e32 v107, 31, v106
	v_add_u32_e32 v102, 0xb0, v178
	v_ashrrev_i32_e32 v103, 31, v102
	v_lshlrev_b64 v[68:69], 12, v[110:111]
	v_lshl_add_u64 v[68:69], v[176:177], 0, v[68:69]
	global_load_dwordx4 v[88:91], v[68:69], off
	global_load_dwordx4 v[84:87], v[68:69], off offset:256
	global_load_dwordx2 v[112:113], v[174:175], off offset:1152
	v_lshlrev_b64 v[68:69], 12, v[106:107]
	v_lshl_add_u64 v[68:69], v[176:177], 0, v[68:69]
	global_load_dwordx4 v[80:83], v[68:69], off
	global_load_dwordx4 v[76:79], v[68:69], off offset:256
	global_load_dwordx2 v[108:109], v[174:175], off offset:1280
	v_lshlrev_b64 v[68:69], 12, v[102:103]
	v_lshl_add_u64 v[68:69], v[176:177], 0, v[68:69]
	global_load_dwordx4 v[72:75], v[68:69], off
	s_nop 0
	global_load_dwordx4 v[68:71], v[68:69], off offset:256
	s_nop 0
	global_load_dwordx2 v[104:105], v[174:175], off offset:1408
	s_waitcnt vmcnt(11)
	v_and_b32_e32 v123, 0xffff0000, v98
	s_waitcnt vmcnt(9)
	v_ffbh_u32_e32 v232, v229
	v_min_u32_e32 v232, 32, v232
	v_lshlrev_b64 v[230:231], v232, v[228:229]
	v_min_u32_e32 v230, 1, v230
	v_or_b32_e32 v230, v231, v230
	v_cvt_f32_u32_e32 v230, v230
	v_sub_u32_e32 v231, 32, v232
	v_ldexp_f32 v230, v230, v231
	v_fmamk_f32 v101, v230, 0x2e000000, v200
	v_div_scale_f32 v118, s[0:1], v101, v101, 1.0
	v_rcp_f32_e32 v119, v118
	s_nop 0
	v_fma_f32 v120, -v118, v119, 1.0
	v_fmac_f32_e32 v119, v120, v119
	v_div_scale_f32 v120, vcc, 1.0, v101, 1.0
	v_mul_f32_e32 v121, v120, v119
	v_fma_f32 v122, -v118, v121, v120
	v_fmac_f32_e32 v121, v122, v119
	v_fma_f32 v118, -v118, v121, v120
	v_div_fmas_f32 v118, v118, v119, v121
	v_div_fixup_f32 v118, v118, v101, 1.0
	v_lshlrev_b32_e32 v120, 16, v96
	v_and_b32_e32 v121, 0xffff0000, v96
	v_lshlrev_b32_e32 v122, 16, v98
	v_lshlrev_b32_e32 v96, 16, v97
	v_and_b32_e32 v97, 0xffff0000, v97
	v_lshlrev_b32_e32 v98, 16, v99
	v_and_b32_e32 v99, 0xffff0000, v99
	v_pk_fma_f32 v[66:67], v[66:67], v[118:119], v[96:97] op_sel_hi:[1,0,1]
	v_pk_fma_f32 v[64:65], v[64:65], v[118:119], v[120:121] op_sel_hi:[1,0,1]
	v_pk_fma_f32 v[62:63], v[62:63], v[118:119], v[98:99] op_sel_hi:[1,0,1]
	v_pk_fma_f32 v[60:61], v[60:61], v[118:119], v[122:123] op_sel_hi:[1,0,1]
	s_and_b64 vcc, exec, s[40:41]
	v_lshl_add_u64 v[98:99], v[116:117], 2, s[8:9]
	s_cbranch_vccnz .LBB0_1038
	v_lshl_add_u64 v[96:97], v[172:173], 2, v[98:99]
	global_store_dwordx4 v[96:97], v[64:67], off
	global_store_dwordx4 v[96:97], v[60:63], off offset:16
	v_lshl_add_u64 v[96:97], s[14:15], 0, v[114:115]
	v_lshl_add_u64 v[96:97], v[172:173], 1, v[96:97]
	s_cbranch_execnz .LBB0_996
